# P2 (mixer-input GEMM) and P5 (gate GEMM, sigmoid) epilogues: lane-transposed packed rows, coalesced stores (same scheme as the up-projection epilogue)
# speedup vs baseline: 1.0364x; 1.0151x over previous
.LBB0_216:
	v_mbcnt_lo_u32_b32 v144, -1, 0
	v_mbcnt_hi_u32_b32 v144, -1, v144
	v_and_b32_e32 v145, 3, v144
	v_lshrrev_b32_e32 v146, 2, v144
	v_lshl_add_u32 v147, v145, 4, v146
	v_lshlrev_b32_e32 v147, 2, v147
	v_readfirstlane_b32 s18, v140
	v_readfirstlane_b32 s19, v142
	s_lshl_b32 vcc_lo, s41, 8
	s_add_i32 s18, vcc_lo, s18
	s_lshl_b32 vcc_lo, s40, 8
	s_or_b32 s19, vcc_lo, s19
	s_mov_b32 vcc_lo, s18
	s_mov_b32 vcc_hi, s19
	v_add_u32_e32 v146, vcc_lo, v146
	v_lshl_add_u32 v145, v145, 3, vcc_hi
	v_lshlrev_b32_e32 v145, 1, v145
	v_mul_u32_u24_e32 v148, 0x1c00, v146
	v_add_u32_e32 v148, v148, v145
	v_cvt_pk_bf16_f32 v126, v126, v127
	v_cvt_pk_bf16_f32 v127, v128, v129
	v_cvt_pk_bf16_f32 v128, v122, v123
	v_cvt_pk_bf16_f32 v129, v124, v125
	ds_bpermute_b32 v152, v147, v126
	ds_bpermute_b32 v153, v147, v127
	ds_bpermute_b32 v154, v147, v128
	ds_bpermute_b32 v155, v147, v129
	v_cvt_pk_bf16_f32 v110, v110, v111
	v_cvt_pk_bf16_f32 v111, v112, v113
	v_cvt_pk_bf16_f32 v112, v106, v107
	v_cvt_pk_bf16_f32 v113, v108, v109
	ds_bpermute_b32 v156, v147, v110
	ds_bpermute_b32 v157, v147, v111
	ds_bpermute_b32 v158, v147, v112
	ds_bpermute_b32 v159, v147, v113
	v_cvt_pk_bf16_f32 v118, v118, v119
	v_cvt_pk_bf16_f32 v119, v120, v121
	v_cvt_pk_bf16_f32 v120, v114, v115
	v_cvt_pk_bf16_f32 v121, v116, v117
	ds_bpermute_b32 v160, v147, v118
	ds_bpermute_b32 v161, v147, v119
	ds_bpermute_b32 v162, v147, v120
	ds_bpermute_b32 v163, v147, v121
	s_waitcnt lgkmcnt(8)
	s_add_u32 s18, s4, 0x0
	s_addc_u32 s19, s5, 0
	global_store_dwordx4 v148, v[152:155], s[18:19]
	v_cvt_pk_bf16_f32 v94, v94, v95
	v_cvt_pk_bf16_f32 v95, v96, v97
	v_cvt_pk_bf16_f32 v96, v90, v91
	v_cvt_pk_bf16_f32 v97, v92, v93
	ds_bpermute_b32 v164, v147, v94
	ds_bpermute_b32 v165, v147, v95
	ds_bpermute_b32 v166, v147, v96
	ds_bpermute_b32 v167, v147, v97
	s_waitcnt lgkmcnt(8)
	global_store_dwordx4 v148, v[156:159], s[18:19] offset:256
	v_cvt_pk_bf16_f32 v102, v102, v103
	v_cvt_pk_bf16_f32 v103, v104, v105
	v_cvt_pk_bf16_f32 v104, v98, v99
	v_cvt_pk_bf16_f32 v105, v100, v101
	ds_bpermute_b32 v168, v147, v102
	ds_bpermute_b32 v169, v147, v103
	ds_bpermute_b32 v170, v147, v104
	ds_bpermute_b32 v171, v147, v105
	s_waitcnt lgkmcnt(8)
	s_add_u32 s18, s4, 0x1c000
	s_addc_u32 s19, s5, 0
	global_store_dwordx4 v148, v[160:163], s[18:19]
	v_cvt_pk_bf16_f32 v78, v78, v79
	v_cvt_pk_bf16_f32 v79, v80, v81
	v_cvt_pk_bf16_f32 v80, v74, v75
	v_cvt_pk_bf16_f32 v81, v76, v77
	ds_bpermute_b32 v172, v147, v78
	ds_bpermute_b32 v173, v147, v79
	ds_bpermute_b32 v174, v147, v80
	ds_bpermute_b32 v175, v147, v81
	s_waitcnt lgkmcnt(8)
	global_store_dwordx4 v148, v[164:167], s[18:19] offset:256
	v_cvt_pk_bf16_f32 v86, v86, v87
	v_cvt_pk_bf16_f32 v87, v88, v89
	v_cvt_pk_bf16_f32 v88, v82, v83
	v_cvt_pk_bf16_f32 v89, v84, v85
	ds_bpermute_b32 v176, v147, v86
	ds_bpermute_b32 v177, v147, v87
	ds_bpermute_b32 v178, v147, v88
	ds_bpermute_b32 v179, v147, v89
	s_waitcnt lgkmcnt(8)
	s_add_u32 s18, s4, 0x38000
	s_addc_u32 s19, s5, 0
	global_store_dwordx4 v148, v[168:171], s[18:19]
	v_cvt_pk_bf16_f32 v70, v70, v71
	v_cvt_pk_bf16_f32 v71, v72, v73
	v_cvt_pk_bf16_f32 v72, v66, v67
	v_cvt_pk_bf16_f32 v73, v68, v69
	ds_bpermute_b32 v186, v147, v70
	ds_bpermute_b32 v187, v147, v71
	ds_bpermute_b32 v188, v147, v72
	ds_bpermute_b32 v189, v147, v73
	s_waitcnt lgkmcnt(8)
	global_store_dwordx4 v148, v[172:175], s[18:19] offset:256
	v_cvt_pk_bf16_f32 v62, v62, v63
	v_cvt_pk_bf16_f32 v63, v64, v65
	v_cvt_pk_bf16_f32 v64, v58, v59
	v_cvt_pk_bf16_f32 v65, v60, v61
	ds_bpermute_b32 v190, v147, v62
	ds_bpermute_b32 v191, v147, v63
	ds_bpermute_b32 v192, v147, v64
	ds_bpermute_b32 v193, v147, v65
	s_waitcnt lgkmcnt(8)
	s_add_u32 s18, s4, 0x54000
	s_addc_u32 s19, s5, 0
	global_store_dwordx4 v148, v[176:179], s[18:19]
	v_cvt_pk_bf16_f32 v46, v46, v47
	v_cvt_pk_bf16_f32 v47, v48, v49
	v_cvt_pk_bf16_f32 v48, v42, v43
	v_cvt_pk_bf16_f32 v49, v44, v45
	ds_bpermute_b32 v212, v147, v46
	ds_bpermute_b32 v213, v147, v47
	ds_bpermute_b32 v214, v147, v48
	ds_bpermute_b32 v215, v147, v49
	s_waitcnt lgkmcnt(8)
	global_store_dwordx4 v148, v[186:189], s[18:19] offset:256
	v_cvt_pk_bf16_f32 v54, v54, v55
	v_cvt_pk_bf16_f32 v55, v56, v57
	v_cvt_pk_bf16_f32 v56, v50, v51
	v_cvt_pk_bf16_f32 v57, v52, v53
	ds_bpermute_b32 v216, v147, v54
	ds_bpermute_b32 v217, v147, v55
	ds_bpermute_b32 v218, v147, v56
	ds_bpermute_b32 v219, v147, v57
	s_waitcnt lgkmcnt(8)
	s_add_u32 s18, s4, 0xe0000
	s_addc_u32 s19, s5, 0
	global_store_dwordx4 v148, v[190:193], s[18:19]
	v_cvt_pk_bf16_f32 v30, v30, v31
	v_cvt_pk_bf16_f32 v31, v32, v33
	v_cvt_pk_bf16_f32 v32, v26, v27
	v_cvt_pk_bf16_f32 v33, v28, v29
	ds_bpermute_b32 v220, v147, v30
	ds_bpermute_b32 v221, v147, v31
	ds_bpermute_b32 v222, v147, v32
	ds_bpermute_b32 v223, v147, v33
	s_waitcnt lgkmcnt(8)
	global_store_dwordx4 v148, v[212:215], s[18:19] offset:256
	v_cvt_pk_bf16_f32 v38, v38, v39
	v_cvt_pk_bf16_f32 v39, v40, v41
	v_cvt_pk_bf16_f32 v40, v34, v35
	v_cvt_pk_bf16_f32 v41, v36, v37
	ds_bpermute_b32 v224, v147, v38
	ds_bpermute_b32 v225, v147, v39
	ds_bpermute_b32 v226, v147, v40
	ds_bpermute_b32 v227, v147, v41
	s_waitcnt lgkmcnt(8)
	s_add_u32 s18, s4, 0xfc000
	s_addc_u32 s19, s5, 0
	global_store_dwordx4 v148, v[216:219], s[18:19]
	v_cvt_pk_bf16_f32 v14, v14, v15
	v_cvt_pk_bf16_f32 v15, v16, v17
	v_cvt_pk_bf16_f32 v16, v10, v11
	v_cvt_pk_bf16_f32 v17, v12, v13
	ds_bpermute_b32 v228, v147, v14
	ds_bpermute_b32 v229, v147, v15
	ds_bpermute_b32 v230, v147, v16
	ds_bpermute_b32 v231, v147, v17
	s_waitcnt lgkmcnt(8)
	global_store_dwordx4 v148, v[220:223], s[18:19] offset:256
	v_cvt_pk_bf16_f32 v22, v22, v23
	v_cvt_pk_bf16_f32 v23, v24, v25
	v_cvt_pk_bf16_f32 v24, v18, v19
	v_cvt_pk_bf16_f32 v25, v20, v21
	ds_bpermute_b32 v232, v147, v22
	ds_bpermute_b32 v233, v147, v23
	ds_bpermute_b32 v234, v147, v24
	ds_bpermute_b32 v235, v147, v25
	s_waitcnt lgkmcnt(8)
	s_add_u32 s18, s4, 0x118000
	s_addc_u32 s19, s5, 0
	global_store_dwordx4 v148, v[224:227], s[18:19]
	v_cvt_pk_bf16_f32 v6, v6, v7
	v_cvt_pk_bf16_f32 v7, v8, v9
	v_cvt_pk_bf16_f32 v8, v2, v3
	v_cvt_pk_bf16_f32 v9, v4, v5
	ds_bpermute_b32 v236, v147, v6
	ds_bpermute_b32 v237, v147, v7
	ds_bpermute_b32 v238, v147, v8
	ds_bpermute_b32 v239, v147, v9
	s_waitcnt lgkmcnt(8)
	global_store_dwordx4 v148, v[228:231], s[18:19] offset:256
	s_waitcnt lgkmcnt(4)
	s_add_u32 s18, s4, 0x134000
	s_addc_u32 s19, s5, 0
	global_store_dwordx4 v148, v[232:235], s[18:19]
	s_waitcnt lgkmcnt(0)
	global_store_dwordx4 v148, v[236:239], s[18:19] offset:256
	s_andn2_b64 vcc, exec, s[38:39]
	s_mov_b64 s[18:19], -1
	s_cbranch_vccnz .LBB0_209
	s_andn2_b64 vcc, exec, s[2:3]
	s_cbranch_vccnz .LBB0_208
	s_barrier
	s_branch .LBB0_208

.LBB0_687:
	v_mbcnt_lo_u32_b32 v140, -1, 0
	v_mbcnt_hi_u32_b32 v140, -1, v140
	v_and_b32_e32 v141, 3, v140
	v_lshrrev_b32_e32 v142, 2, v140
	v_lshl_add_u32 v143, v141, 4, v142
	v_lshlrev_b32_e32 v143, 2, v143
	v_readfirstlane_b32 vcc_lo, v144
	v_readfirstlane_b32 vcc_hi, v146
	s_lshl_b32 s18, s18, 8
	s_lshl_b32 s19, s19, 8
	s_add_i32 vcc_lo, s18, vcc_lo
	s_or_b32 vcc_hi, s19, vcc_hi
	v_add_u32_e32 v142, vcc_lo, v142
	v_lshl_add_u32 v141, v141, 3, vcc_hi
	v_lshlrev_b32_e32 v141, 1, v141
	v_mul_u32_u24_e32 v148, 0x1800, v142
	v_add_u32_e32 v148, v148, v141
	v_mul_f32_e32 v126, 0xbfb8aa3b, v126
	v_mul_f32_e32 v127, 0xbfb8aa3b, v127
	v_mul_f32_e32 v128, 0xbfb8aa3b, v128
	v_mul_f32_e32 v129, 0xbfb8aa3b, v129
	v_mul_f32_e32 v122, 0xbfb8aa3b, v122
	v_mul_f32_e32 v123, 0xbfb8aa3b, v123
	v_mul_f32_e32 v124, 0xbfb8aa3b, v124
	v_mul_f32_e32 v125, 0xbfb8aa3b, v125
	v_exp_f32_e32 v126, v126
	v_exp_f32_e32 v127, v127
	v_exp_f32_e32 v128, v128
	v_exp_f32_e32 v129, v129
	v_exp_f32_e32 v122, v122
	v_exp_f32_e32 v123, v123
	v_exp_f32_e32 v124, v124
	v_exp_f32_e32 v125, v125
	v_add_f32_e32 v126, 1.0, v126
	v_add_f32_e32 v127, 1.0, v127
	v_add_f32_e32 v128, 1.0, v128
	v_add_f32_e32 v129, 1.0, v129
	v_add_f32_e32 v122, 1.0, v122
	v_add_f32_e32 v123, 1.0, v123
	v_add_f32_e32 v124, 1.0, v124
	v_add_f32_e32 v125, 1.0, v125
	v_rcp_f32_e32 v126, v126
	v_rcp_f32_e32 v127, v127
	v_rcp_f32_e32 v128, v128
	v_rcp_f32_e32 v129, v129
	v_rcp_f32_e32 v122, v122
	v_rcp_f32_e32 v123, v123
	v_rcp_f32_e32 v124, v124
	v_rcp_f32_e32 v125, v125
	v_cvt_pk_bf16_f32 v126, v126, v127
	v_cvt_pk_bf16_f32 v127, v128, v129
	v_cvt_pk_bf16_f32 v128, v122, v123
	v_cvt_pk_bf16_f32 v129, v124, v125
	ds_bpermute_b32 v152, v143, v126
	ds_bpermute_b32 v153, v143, v127
	ds_bpermute_b32 v154, v143, v128
	ds_bpermute_b32 v155, v143, v129
	v_mul_f32_e32 v118, 0xbfb8aa3b, v118
	v_mul_f32_e32 v119, 0xbfb8aa3b, v119
	v_mul_f32_e32 v120, 0xbfb8aa3b, v120
	v_mul_f32_e32 v121, 0xbfb8aa3b, v121
	v_mul_f32_e32 v114, 0xbfb8aa3b, v114
	v_mul_f32_e32 v115, 0xbfb8aa3b, v115
	v_mul_f32_e32 v116, 0xbfb8aa3b, v116
	v_mul_f32_e32 v117, 0xbfb8aa3b, v117
	v_exp_f32_e32 v118, v118
	v_exp_f32_e32 v119, v119
	v_exp_f32_e32 v120, v120
	v_exp_f32_e32 v121, v121
	v_exp_f32_e32 v114, v114
	v_exp_f32_e32 v115, v115
	v_exp_f32_e32 v116, v116
	v_exp_f32_e32 v117, v117
	v_add_f32_e32 v118, 1.0, v118
	v_add_f32_e32 v119, 1.0, v119
	v_add_f32_e32 v120, 1.0, v120
	v_add_f32_e32 v121, 1.0, v121
	v_add_f32_e32 v114, 1.0, v114
	v_add_f32_e32 v115, 1.0, v115
	v_add_f32_e32 v116, 1.0, v116
	v_add_f32_e32 v117, 1.0, v117
	v_rcp_f32_e32 v118, v118
	v_rcp_f32_e32 v119, v119
	v_rcp_f32_e32 v120, v120
	v_rcp_f32_e32 v121, v121
	v_rcp_f32_e32 v114, v114
	v_rcp_f32_e32 v115, v115
	v_rcp_f32_e32 v116, v116
	v_rcp_f32_e32 v117, v117
	v_cvt_pk_bf16_f32 v118, v118, v119
	v_cvt_pk_bf16_f32 v119, v120, v121
	v_cvt_pk_bf16_f32 v120, v114, v115
	v_cvt_pk_bf16_f32 v121, v116, v117
	ds_bpermute_b32 v156, v143, v118
	ds_bpermute_b32 v157, v143, v119
	ds_bpermute_b32 v158, v143, v120
	ds_bpermute_b32 v159, v143, v121
	v_mul_f32_e32 v110, 0xbfb8aa3b, v110
	v_mul_f32_e32 v111, 0xbfb8aa3b, v111
	v_mul_f32_e32 v112, 0xbfb8aa3b, v112
	v_mul_f32_e32 v113, 0xbfb8aa3b, v113
	v_mul_f32_e32 v106, 0xbfb8aa3b, v106
	v_mul_f32_e32 v107, 0xbfb8aa3b, v107
	v_mul_f32_e32 v108, 0xbfb8aa3b, v108
	v_mul_f32_e32 v109, 0xbfb8aa3b, v109
	v_exp_f32_e32 v110, v110
	v_exp_f32_e32 v111, v111
	v_exp_f32_e32 v112, v112
	v_exp_f32_e32 v113, v113
	v_exp_f32_e32 v106, v106
	v_exp_f32_e32 v107, v107
	v_exp_f32_e32 v108, v108
	v_exp_f32_e32 v109, v109
	v_add_f32_e32 v110, 1.0, v110
	v_add_f32_e32 v111, 1.0, v111
	v_add_f32_e32 v112, 1.0, v112
	v_add_f32_e32 v113, 1.0, v113
	v_add_f32_e32 v106, 1.0, v106
	v_add_f32_e32 v107, 1.0, v107
	v_add_f32_e32 v108, 1.0, v108
	v_add_f32_e32 v109, 1.0, v109
	v_rcp_f32_e32 v110, v110
	v_rcp_f32_e32 v111, v111
	v_rcp_f32_e32 v112, v112
	v_rcp_f32_e32 v113, v113
	v_rcp_f32_e32 v106, v106
	v_rcp_f32_e32 v107, v107
	v_rcp_f32_e32 v108, v108
	v_rcp_f32_e32 v109, v109
	v_cvt_pk_bf16_f32 v110, v110, v111
	v_cvt_pk_bf16_f32 v111, v112, v113
	v_cvt_pk_bf16_f32 v112, v106, v107
	v_cvt_pk_bf16_f32 v113, v108, v109
	ds_bpermute_b32 v160, v143, v110
	ds_bpermute_b32 v161, v143, v111
	ds_bpermute_b32 v162, v143, v112
	ds_bpermute_b32 v163, v143, v113
	s_waitcnt lgkmcnt(8)
	s_add_u32 s18, s4, 0x0
	s_addc_u32 s19, s5, 0
	global_store_dwordx4 v148, v[152:155], s[18:19]
	v_mul_f32_e32 v102, 0xbfb8aa3b, v102
	v_mul_f32_e32 v103, 0xbfb8aa3b, v103
	v_mul_f32_e32 v104, 0xbfb8aa3b, v104
	v_mul_f32_e32 v105, 0xbfb8aa3b, v105
	v_mul_f32_e32 v98, 0xbfb8aa3b, v98
	v_mul_f32_e32 v99, 0xbfb8aa3b, v99
	v_mul_f32_e32 v100, 0xbfb8aa3b, v100
	v_mul_f32_e32 v101, 0xbfb8aa3b, v101
	v_exp_f32_e32 v102, v102
	v_exp_f32_e32 v103, v103
	v_exp_f32_e32 v104, v104
	v_exp_f32_e32 v105, v105
	v_exp_f32_e32 v98, v98
	v_exp_f32_e32 v99, v99
	v_exp_f32_e32 v100, v100
	v_exp_f32_e32 v101, v101
	v_add_f32_e32 v102, 1.0, v102
	v_add_f32_e32 v103, 1.0, v103
	v_add_f32_e32 v104, 1.0, v104
	v_add_f32_e32 v105, 1.0, v105
	v_add_f32_e32 v98, 1.0, v98
	v_add_f32_e32 v99, 1.0, v99
	v_add_f32_e32 v100, 1.0, v100
	v_add_f32_e32 v101, 1.0, v101
	v_rcp_f32_e32 v102, v102
	v_rcp_f32_e32 v103, v103
	v_rcp_f32_e32 v104, v104
	v_rcp_f32_e32 v105, v105
	v_rcp_f32_e32 v98, v98
	v_rcp_f32_e32 v99, v99
	v_rcp_f32_e32 v100, v100
	v_rcp_f32_e32 v101, v101
	v_cvt_pk_bf16_f32 v102, v102, v103
	v_cvt_pk_bf16_f32 v103, v104, v105
	v_cvt_pk_bf16_f32 v104, v98, v99
	v_cvt_pk_bf16_f32 v105, v100, v101
	ds_bpermute_b32 v164, v143, v102
	ds_bpermute_b32 v165, v143, v103
	ds_bpermute_b32 v166, v143, v104
	ds_bpermute_b32 v167, v143, v105
	s_waitcnt lgkmcnt(8)
	global_store_dwordx4 v148, v[156:159], s[18:19] offset:256
	v_mul_f32_e32 v94, 0xbfb8aa3b, v94
	v_mul_f32_e32 v95, 0xbfb8aa3b, v95
	v_mul_f32_e32 v96, 0xbfb8aa3b, v96
	v_mul_f32_e32 v97, 0xbfb8aa3b, v97
	v_mul_f32_e32 v90, 0xbfb8aa3b, v90
	v_mul_f32_e32 v91, 0xbfb8aa3b, v91
	v_mul_f32_e32 v92, 0xbfb8aa3b, v92
	v_mul_f32_e32 v93, 0xbfb8aa3b, v93
	v_exp_f32_e32 v94, v94
	v_exp_f32_e32 v95, v95
	v_exp_f32_e32 v96, v96
	v_exp_f32_e32 v97, v97
	v_exp_f32_e32 v90, v90
	v_exp_f32_e32 v91, v91
	v_exp_f32_e32 v92, v92
	v_exp_f32_e32 v93, v93
	v_add_f32_e32 v94, 1.0, v94
	v_add_f32_e32 v95, 1.0, v95
	v_add_f32_e32 v96, 1.0, v96
	v_add_f32_e32 v97, 1.0, v97
	v_add_f32_e32 v90, 1.0, v90
	v_add_f32_e32 v91, 1.0, v91
	v_add_f32_e32 v92, 1.0, v92
	v_add_f32_e32 v93, 1.0, v93
	v_rcp_f32_e32 v94, v94
	v_rcp_f32_e32 v95, v95
	v_rcp_f32_e32 v96, v96
	v_rcp_f32_e32 v97, v97
	v_rcp_f32_e32 v90, v90
	v_rcp_f32_e32 v91, v91
	v_rcp_f32_e32 v92, v92
	v_rcp_f32_e32 v93, v93
	v_cvt_pk_bf16_f32 v94, v94, v95
	v_cvt_pk_bf16_f32 v95, v96, v97
	v_cvt_pk_bf16_f32 v96, v90, v91
	v_cvt_pk_bf16_f32 v97, v92, v93
	ds_bpermute_b32 v168, v143, v94
	ds_bpermute_b32 v169, v143, v95
	ds_bpermute_b32 v170, v143, v96
	ds_bpermute_b32 v171, v143, v97
	s_waitcnt lgkmcnt(8)
	s_add_u32 s18, s4, 0x18000
	s_addc_u32 s19, s5, 0
	global_store_dwordx4 v148, v[160:163], s[18:19]
	v_mul_f32_e32 v86, 0xbfb8aa3b, v86
	v_mul_f32_e32 v87, 0xbfb8aa3b, v87
	v_mul_f32_e32 v88, 0xbfb8aa3b, v88
	v_mul_f32_e32 v89, 0xbfb8aa3b, v89
	v_mul_f32_e32 v82, 0xbfb8aa3b, v82
	v_mul_f32_e32 v83, 0xbfb8aa3b, v83
	v_mul_f32_e32 v84, 0xbfb8aa3b, v84
	v_mul_f32_e32 v85, 0xbfb8aa3b, v85
	v_exp_f32_e32 v86, v86
	v_exp_f32_e32 v87, v87
	v_exp_f32_e32 v88, v88
	v_exp_f32_e32 v89, v89
	v_exp_f32_e32 v82, v82
	v_exp_f32_e32 v83, v83
	v_exp_f32_e32 v84, v84
	v_exp_f32_e32 v85, v85
	v_add_f32_e32 v86, 1.0, v86
	v_add_f32_e32 v87, 1.0, v87
	v_add_f32_e32 v88, 1.0, v88
	v_add_f32_e32 v89, 1.0, v89
	v_add_f32_e32 v82, 1.0, v82
	v_add_f32_e32 v83, 1.0, v83
	v_add_f32_e32 v84, 1.0, v84
	v_add_f32_e32 v85, 1.0, v85
	v_rcp_f32_e32 v86, v86
	v_rcp_f32_e32 v87, v87
	v_rcp_f32_e32 v88, v88
	v_rcp_f32_e32 v89, v89
	v_rcp_f32_e32 v82, v82
	v_rcp_f32_e32 v83, v83
	v_rcp_f32_e32 v84, v84
	v_rcp_f32_e32 v85, v85
	v_cvt_pk_bf16_f32 v86, v86, v87
	v_cvt_pk_bf16_f32 v87, v88, v89
	v_cvt_pk_bf16_f32 v88, v82, v83
	v_cvt_pk_bf16_f32 v89, v84, v85
	ds_bpermute_b32 v172, v143, v86
	ds_bpermute_b32 v173, v143, v87
	ds_bpermute_b32 v174, v143, v88
	ds_bpermute_b32 v175, v143, v89
	s_waitcnt lgkmcnt(8)
	global_store_dwordx4 v148, v[164:167], s[18:19] offset:256
	v_mul_f32_e32 v78, 0xbfb8aa3b, v78
	v_mul_f32_e32 v79, 0xbfb8aa3b, v79
	v_mul_f32_e32 v80, 0xbfb8aa3b, v80
	v_mul_f32_e32 v81, 0xbfb8aa3b, v81
	v_mul_f32_e32 v74, 0xbfb8aa3b, v74
	v_mul_f32_e32 v75, 0xbfb8aa3b, v75
	v_mul_f32_e32 v76, 0xbfb8aa3b, v76
	v_mul_f32_e32 v77, 0xbfb8aa3b, v77
	v_exp_f32_e32 v78, v78
	v_exp_f32_e32 v79, v79
	v_exp_f32_e32 v80, v80
	v_exp_f32_e32 v81, v81
	v_exp_f32_e32 v74, v74
	v_exp_f32_e32 v75, v75
	v_exp_f32_e32 v76, v76
	v_exp_f32_e32 v77, v77
	v_add_f32_e32 v78, 1.0, v78
	v_add_f32_e32 v79, 1.0, v79
	v_add_f32_e32 v80, 1.0, v80
	v_add_f32_e32 v81, 1.0, v81
	v_add_f32_e32 v74, 1.0, v74
	v_add_f32_e32 v75, 1.0, v75
	v_add_f32_e32 v76, 1.0, v76
	v_add_f32_e32 v77, 1.0, v77
	v_rcp_f32_e32 v78, v78
	v_rcp_f32_e32 v79, v79
	v_rcp_f32_e32 v80, v80
	v_rcp_f32_e32 v81, v81
	v_rcp_f32_e32 v74, v74
	v_rcp_f32_e32 v75, v75
	v_rcp_f32_e32 v76, v76
	v_rcp_f32_e32 v77, v77
	v_cvt_pk_bf16_f32 v78, v78, v79
	v_cvt_pk_bf16_f32 v79, v80, v81
	v_cvt_pk_bf16_f32 v80, v74, v75
	v_cvt_pk_bf16_f32 v81, v76, v77
	ds_bpermute_b32 v176, v143, v78
	ds_bpermute_b32 v177, v143, v79
	ds_bpermute_b32 v178, v143, v80
	ds_bpermute_b32 v179, v143, v81
	s_waitcnt lgkmcnt(8)
	s_add_u32 s18, s4, 0x30000
	s_addc_u32 s19, s5, 0
	global_store_dwordx4 v148, v[168:171], s[18:19]
	v_mul_f32_e32 v70, 0xbfb8aa3b, v70
	v_mul_f32_e32 v71, 0xbfb8aa3b, v71
	v_mul_f32_e32 v72, 0xbfb8aa3b, v72
	v_mul_f32_e32 v73, 0xbfb8aa3b, v73
	v_mul_f32_e32 v66, 0xbfb8aa3b, v66
	v_mul_f32_e32 v67, 0xbfb8aa3b, v67
	v_mul_f32_e32 v68, 0xbfb8aa3b, v68
	v_mul_f32_e32 v69, 0xbfb8aa3b, v69
	v_exp_f32_e32 v70, v70
	v_exp_f32_e32 v71, v71
	v_exp_f32_e32 v72, v72
	v_exp_f32_e32 v73, v73
	v_exp_f32_e32 v66, v66
	v_exp_f32_e32 v67, v67
	v_exp_f32_e32 v68, v68
	v_exp_f32_e32 v69, v69
	v_add_f32_e32 v70, 1.0, v70
	v_add_f32_e32 v71, 1.0, v71
	v_add_f32_e32 v72, 1.0, v72
	v_add_f32_e32 v73, 1.0, v73
	v_add_f32_e32 v66, 1.0, v66
	v_add_f32_e32 v67, 1.0, v67
	v_add_f32_e32 v68, 1.0, v68
	v_add_f32_e32 v69, 1.0, v69
	v_rcp_f32_e32 v70, v70
	v_rcp_f32_e32 v71, v71
	v_rcp_f32_e32 v72, v72
	v_rcp_f32_e32 v73, v73
	v_rcp_f32_e32 v66, v66
	v_rcp_f32_e32 v67, v67
	v_rcp_f32_e32 v68, v68
	v_rcp_f32_e32 v69, v69
	v_cvt_pk_bf16_f32 v70, v70, v71
	v_cvt_pk_bf16_f32 v71, v72, v73
	v_cvt_pk_bf16_f32 v72, v66, v67
	v_cvt_pk_bf16_f32 v73, v68, v69
	ds_bpermute_b32 v186, v143, v70
	ds_bpermute_b32 v187, v143, v71
	ds_bpermute_b32 v188, v143, v72
	ds_bpermute_b32 v189, v143, v73
	s_waitcnt lgkmcnt(8)
	global_store_dwordx4 v148, v[172:175], s[18:19] offset:256
	v_mul_f32_e32 v62, 0xbfb8aa3b, v62
	v_mul_f32_e32 v63, 0xbfb8aa3b, v63
	v_mul_f32_e32 v64, 0xbfb8aa3b, v64
	v_mul_f32_e32 v65, 0xbfb8aa3b, v65
	v_mul_f32_e32 v58, 0xbfb8aa3b, v58
	v_mul_f32_e32 v59, 0xbfb8aa3b, v59
	v_mul_f32_e32 v60, 0xbfb8aa3b, v60
	v_mul_f32_e32 v61, 0xbfb8aa3b, v61
	v_exp_f32_e32 v62, v62
	v_exp_f32_e32 v63, v63
	v_exp_f32_e32 v64, v64
	v_exp_f32_e32 v65, v65
	v_exp_f32_e32 v58, v58
	v_exp_f32_e32 v59, v59
	v_exp_f32_e32 v60, v60
	v_exp_f32_e32 v61, v61
	v_add_f32_e32 v62, 1.0, v62
	v_add_f32_e32 v63, 1.0, v63
	v_add_f32_e32 v64, 1.0, v64
	v_add_f32_e32 v65, 1.0, v65
	v_add_f32_e32 v58, 1.0, v58
	v_add_f32_e32 v59, 1.0, v59
	v_add_f32_e32 v60, 1.0, v60
	v_add_f32_e32 v61, 1.0, v61
	v_rcp_f32_e32 v62, v62
	v_rcp_f32_e32 v63, v63
	v_rcp_f32_e32 v64, v64
	v_rcp_f32_e32 v65, v65
	v_rcp_f32_e32 v58, v58
	v_rcp_f32_e32 v59, v59
	v_rcp_f32_e32 v60, v60
	v_rcp_f32_e32 v61, v61
	v_cvt_pk_bf16_f32 v62, v62, v63
	v_cvt_pk_bf16_f32 v63, v64, v65
	v_cvt_pk_bf16_f32 v64, v58, v59
	v_cvt_pk_bf16_f32 v65, v60, v61
	ds_bpermute_b32 v190, v143, v62
	ds_bpermute_b32 v191, v143, v63
	ds_bpermute_b32 v192, v143, v64
	ds_bpermute_b32 v193, v143, v65
	s_waitcnt lgkmcnt(8)
	s_add_u32 s18, s4, 0x48000
	s_addc_u32 s19, s5, 0
	global_store_dwordx4 v148, v[176:179], s[18:19]
	v_mul_f32_e32 v54, 0xbfb8aa3b, v54
	v_mul_f32_e32 v55, 0xbfb8aa3b, v55
	v_mul_f32_e32 v56, 0xbfb8aa3b, v56
	v_mul_f32_e32 v57, 0xbfb8aa3b, v57
	v_mul_f32_e32 v50, 0xbfb8aa3b, v50
	v_mul_f32_e32 v51, 0xbfb8aa3b, v51
	v_mul_f32_e32 v52, 0xbfb8aa3b, v52
	v_mul_f32_e32 v53, 0xbfb8aa3b, v53
	v_exp_f32_e32 v54, v54
	v_exp_f32_e32 v55, v55
	v_exp_f32_e32 v56, v56
	v_exp_f32_e32 v57, v57
	v_exp_f32_e32 v50, v50
	v_exp_f32_e32 v51, v51
	v_exp_f32_e32 v52, v52
	v_exp_f32_e32 v53, v53
	v_add_f32_e32 v54, 1.0, v54
	v_add_f32_e32 v55, 1.0, v55
	v_add_f32_e32 v56, 1.0, v56
	v_add_f32_e32 v57, 1.0, v57
	v_add_f32_e32 v50, 1.0, v50
	v_add_f32_e32 v51, 1.0, v51
	v_add_f32_e32 v52, 1.0, v52
	v_add_f32_e32 v53, 1.0, v53
	v_rcp_f32_e32 v54, v54
	v_rcp_f32_e32 v55, v55
	v_rcp_f32_e32 v56, v56
	v_rcp_f32_e32 v57, v57
	v_rcp_f32_e32 v50, v50
	v_rcp_f32_e32 v51, v51
	v_rcp_f32_e32 v52, v52
	v_rcp_f32_e32 v53, v53
	v_cvt_pk_bf16_f32 v54, v54, v55
	v_cvt_pk_bf16_f32 v55, v56, v57
	v_cvt_pk_bf16_f32 v56, v50, v51
	v_cvt_pk_bf16_f32 v57, v52, v53
	ds_bpermute_b32 v212, v143, v54
	ds_bpermute_b32 v213, v143, v55
	ds_bpermute_b32 v214, v143, v56
	ds_bpermute_b32 v215, v143, v57
	s_waitcnt lgkmcnt(8)
	global_store_dwordx4 v148, v[186:189], s[18:19] offset:256
	v_mul_f32_e32 v46, 0xbfb8aa3b, v46
	v_mul_f32_e32 v47, 0xbfb8aa3b, v47
	v_mul_f32_e32 v48, 0xbfb8aa3b, v48
	v_mul_f32_e32 v49, 0xbfb8aa3b, v49
	v_mul_f32_e32 v42, 0xbfb8aa3b, v42
	v_mul_f32_e32 v43, 0xbfb8aa3b, v43
	v_mul_f32_e32 v44, 0xbfb8aa3b, v44
	v_mul_f32_e32 v45, 0xbfb8aa3b, v45
	v_exp_f32_e32 v46, v46
	v_exp_f32_e32 v47, v47
	v_exp_f32_e32 v48, v48
	v_exp_f32_e32 v49, v49
	v_exp_f32_e32 v42, v42
	v_exp_f32_e32 v43, v43
	v_exp_f32_e32 v44, v44
	v_exp_f32_e32 v45, v45
	v_add_f32_e32 v46, 1.0, v46
	v_add_f32_e32 v47, 1.0, v47
	v_add_f32_e32 v48, 1.0, v48
	v_add_f32_e32 v49, 1.0, v49
	v_add_f32_e32 v42, 1.0, v42
	v_add_f32_e32 v43, 1.0, v43
	v_add_f32_e32 v44, 1.0, v44
	v_add_f32_e32 v45, 1.0, v45
	v_rcp_f32_e32 v46, v46
	v_rcp_f32_e32 v47, v47
	v_rcp_f32_e32 v48, v48
	v_rcp_f32_e32 v49, v49
	v_rcp_f32_e32 v42, v42
	v_rcp_f32_e32 v43, v43
	v_rcp_f32_e32 v44, v44
	v_rcp_f32_e32 v45, v45
	v_cvt_pk_bf16_f32 v46, v46, v47
	v_cvt_pk_bf16_f32 v47, v48, v49
	v_cvt_pk_bf16_f32 v48, v42, v43
	v_cvt_pk_bf16_f32 v49, v44, v45
	ds_bpermute_b32 v216, v143, v46
	ds_bpermute_b32 v217, v143, v47
	ds_bpermute_b32 v218, v143, v48
	ds_bpermute_b32 v219, v143, v49
	s_waitcnt lgkmcnt(8)
	s_add_u32 s18, s4, 0xc0000
	s_addc_u32 s19, s5, 0
	global_store_dwordx4 v148, v[190:193], s[18:19]
	v_mul_f32_e32 v38, 0xbfb8aa3b, v38
	v_mul_f32_e32 v39, 0xbfb8aa3b, v39
	v_mul_f32_e32 v40, 0xbfb8aa3b, v40
	v_mul_f32_e32 v41, 0xbfb8aa3b, v41
	v_mul_f32_e32 v34, 0xbfb8aa3b, v34
	v_mul_f32_e32 v35, 0xbfb8aa3b, v35
	v_mul_f32_e32 v36, 0xbfb8aa3b, v36
	v_mul_f32_e32 v37, 0xbfb8aa3b, v37
	v_exp_f32_e32 v38, v38
	v_exp_f32_e32 v39, v39
	v_exp_f32_e32 v40, v40
	v_exp_f32_e32 v41, v41
	v_exp_f32_e32 v34, v34
	v_exp_f32_e32 v35, v35
	v_exp_f32_e32 v36, v36
	v_exp_f32_e32 v37, v37
	v_add_f32_e32 v38, 1.0, v38
	v_add_f32_e32 v39, 1.0, v39
	v_add_f32_e32 v40, 1.0, v40
	v_add_f32_e32 v41, 1.0, v41
	v_add_f32_e32 v34, 1.0, v34
	v_add_f32_e32 v35, 1.0, v35
	v_add_f32_e32 v36, 1.0, v36
	v_add_f32_e32 v37, 1.0, v37
	v_rcp_f32_e32 v38, v38
	v_rcp_f32_e32 v39, v39
	v_rcp_f32_e32 v40, v40
	v_rcp_f32_e32 v41, v41
	v_rcp_f32_e32 v34, v34
	v_rcp_f32_e32 v35, v35
	v_rcp_f32_e32 v36, v36
	v_rcp_f32_e32 v37, v37
	v_cvt_pk_bf16_f32 v38, v38, v39
	v_cvt_pk_bf16_f32 v39, v40, v41
	v_cvt_pk_bf16_f32 v40, v34, v35
	v_cvt_pk_bf16_f32 v41, v36, v37
	ds_bpermute_b32 v220, v143, v38
	ds_bpermute_b32 v221, v143, v39
	ds_bpermute_b32 v222, v143, v40
	ds_bpermute_b32 v223, v143, v41
	s_waitcnt lgkmcnt(8)
	global_store_dwordx4 v148, v[212:215], s[18:19] offset:256
	v_mul_f32_e32 v30, 0xbfb8aa3b, v30
	v_mul_f32_e32 v31, 0xbfb8aa3b, v31
	v_mul_f32_e32 v32, 0xbfb8aa3b, v32
	v_mul_f32_e32 v33, 0xbfb8aa3b, v33
	v_mul_f32_e32 v26, 0xbfb8aa3b, v26
	v_mul_f32_e32 v27, 0xbfb8aa3b, v27
	v_mul_f32_e32 v28, 0xbfb8aa3b, v28
	v_mul_f32_e32 v29, 0xbfb8aa3b, v29
	v_exp_f32_e32 v30, v30
	v_exp_f32_e32 v31, v31
	v_exp_f32_e32 v32, v32
	v_exp_f32_e32 v33, v33
	v_exp_f32_e32 v26, v26
	v_exp_f32_e32 v27, v27
	v_exp_f32_e32 v28, v28
	v_exp_f32_e32 v29, v29
	v_add_f32_e32 v30, 1.0, v30
	v_add_f32_e32 v31, 1.0, v31
	v_add_f32_e32 v32, 1.0, v32
	v_add_f32_e32 v33, 1.0, v33
	v_add_f32_e32 v26, 1.0, v26
	v_add_f32_e32 v27, 1.0, v27
	v_add_f32_e32 v28, 1.0, v28
	v_add_f32_e32 v29, 1.0, v29
	v_rcp_f32_e32 v30, v30
	v_rcp_f32_e32 v31, v31
	v_rcp_f32_e32 v32, v32
	v_rcp_f32_e32 v33, v33
	v_rcp_f32_e32 v26, v26
	v_rcp_f32_e32 v27, v27
	v_rcp_f32_e32 v28, v28
	v_rcp_f32_e32 v29, v29
	v_cvt_pk_bf16_f32 v30, v30, v31
	v_cvt_pk_bf16_f32 v31, v32, v33
	v_cvt_pk_bf16_f32 v32, v26, v27
	v_cvt_pk_bf16_f32 v33, v28, v29
	ds_bpermute_b32 v224, v143, v30
	ds_bpermute_b32 v225, v143, v31
	ds_bpermute_b32 v226, v143, v32
	ds_bpermute_b32 v227, v143, v33
	s_waitcnt lgkmcnt(8)
	s_add_u32 s18, s4, 0xd8000
	s_addc_u32 s19, s5, 0
	global_store_dwordx4 v148, v[216:219], s[18:19]
	v_mul_f32_e32 v22, 0xbfb8aa3b, v22
	v_mul_f32_e32 v23, 0xbfb8aa3b, v23
	v_mul_f32_e32 v24, 0xbfb8aa3b, v24
	v_mul_f32_e32 v25, 0xbfb8aa3b, v25
	v_mul_f32_e32 v18, 0xbfb8aa3b, v18
	v_mul_f32_e32 v19, 0xbfb8aa3b, v19
	v_mul_f32_e32 v20, 0xbfb8aa3b, v20
	v_mul_f32_e32 v21, 0xbfb8aa3b, v21
	v_exp_f32_e32 v22, v22
	v_exp_f32_e32 v23, v23
	v_exp_f32_e32 v24, v24
	v_exp_f32_e32 v25, v25
	v_exp_f32_e32 v18, v18
	v_exp_f32_e32 v19, v19
	v_exp_f32_e32 v20, v20
	v_exp_f32_e32 v21, v21
	v_add_f32_e32 v22, 1.0, v22
	v_add_f32_e32 v23, 1.0, v23
	v_add_f32_e32 v24, 1.0, v24
	v_add_f32_e32 v25, 1.0, v25
	v_add_f32_e32 v18, 1.0, v18
	v_add_f32_e32 v19, 1.0, v19
	v_add_f32_e32 v20, 1.0, v20
	v_add_f32_e32 v21, 1.0, v21
	v_rcp_f32_e32 v22, v22
	v_rcp_f32_e32 v23, v23
	v_rcp_f32_e32 v24, v24
	v_rcp_f32_e32 v25, v25
	v_rcp_f32_e32 v18, v18
	v_rcp_f32_e32 v19, v19
	v_rcp_f32_e32 v20, v20
	v_rcp_f32_e32 v21, v21
	v_cvt_pk_bf16_f32 v22, v22, v23
	v_cvt_pk_bf16_f32 v23, v24, v25
	v_cvt_pk_bf16_f32 v24, v18, v19
	v_cvt_pk_bf16_f32 v25, v20, v21
	ds_bpermute_b32 v228, v143, v22
	ds_bpermute_b32 v229, v143, v23
	ds_bpermute_b32 v230, v143, v24
	ds_bpermute_b32 v231, v143, v25
	s_waitcnt lgkmcnt(8)
	global_store_dwordx4 v148, v[220:223], s[18:19] offset:256
	v_mul_f32_e32 v14, 0xbfb8aa3b, v14
	v_mul_f32_e32 v15, 0xbfb8aa3b, v15
	v_mul_f32_e32 v16, 0xbfb8aa3b, v16
	v_mul_f32_e32 v17, 0xbfb8aa3b, v17
	v_mul_f32_e32 v10, 0xbfb8aa3b, v10
	v_mul_f32_e32 v11, 0xbfb8aa3b, v11
	v_mul_f32_e32 v12, 0xbfb8aa3b, v12
	v_mul_f32_e32 v13, 0xbfb8aa3b, v13
	v_exp_f32_e32 v14, v14
	v_exp_f32_e32 v15, v15
	v_exp_f32_e32 v16, v16
	v_exp_f32_e32 v17, v17
	v_exp_f32_e32 v10, v10
	v_exp_f32_e32 v11, v11
	v_exp_f32_e32 v12, v12
	v_exp_f32_e32 v13, v13
	v_add_f32_e32 v14, 1.0, v14
	v_add_f32_e32 v15, 1.0, v15
	v_add_f32_e32 v16, 1.0, v16
	v_add_f32_e32 v17, 1.0, v17
	v_add_f32_e32 v10, 1.0, v10
	v_add_f32_e32 v11, 1.0, v11
	v_add_f32_e32 v12, 1.0, v12
	v_add_f32_e32 v13, 1.0, v13
	v_rcp_f32_e32 v14, v14
	v_rcp_f32_e32 v15, v15
	v_rcp_f32_e32 v16, v16
	v_rcp_f32_e32 v17, v17
	v_rcp_f32_e32 v10, v10
	v_rcp_f32_e32 v11, v11
	v_rcp_f32_e32 v12, v12
	v_rcp_f32_e32 v13, v13
	v_cvt_pk_bf16_f32 v14, v14, v15
	v_cvt_pk_bf16_f32 v15, v16, v17
	v_cvt_pk_bf16_f32 v16, v10, v11
	v_cvt_pk_bf16_f32 v17, v12, v13
	ds_bpermute_b32 v232, v143, v14
	ds_bpermute_b32 v233, v143, v15
	ds_bpermute_b32 v234, v143, v16
	ds_bpermute_b32 v235, v143, v17
	s_waitcnt lgkmcnt(8)
	s_add_u32 s18, s4, 0xf0000
	s_addc_u32 s19, s5, 0
	global_store_dwordx4 v148, v[224:227], s[18:19]
	v_mul_f32_e32 v6, 0xbfb8aa3b, v6
	v_mul_f32_e32 v7, 0xbfb8aa3b, v7
	v_mul_f32_e32 v8, 0xbfb8aa3b, v8
	v_mul_f32_e32 v9, 0xbfb8aa3b, v9
	v_mul_f32_e32 v2, 0xbfb8aa3b, v2
	v_mul_f32_e32 v3, 0xbfb8aa3b, v3
	v_mul_f32_e32 v4, 0xbfb8aa3b, v4
	v_mul_f32_e32 v5, 0xbfb8aa3b, v5
	v_exp_f32_e32 v6, v6
	v_exp_f32_e32 v7, v7
	v_exp_f32_e32 v8, v8
	v_exp_f32_e32 v9, v9
	v_exp_f32_e32 v2, v2
	v_exp_f32_e32 v3, v3
	v_exp_f32_e32 v4, v4
	v_exp_f32_e32 v5, v5
	v_add_f32_e32 v6, 1.0, v6
	v_add_f32_e32 v7, 1.0, v7
	v_add_f32_e32 v8, 1.0, v8
	v_add_f32_e32 v9, 1.0, v9
	v_add_f32_e32 v2, 1.0, v2
	v_add_f32_e32 v3, 1.0, v3
	v_add_f32_e32 v4, 1.0, v4
	v_add_f32_e32 v5, 1.0, v5
	v_rcp_f32_e32 v6, v6
	v_rcp_f32_e32 v7, v7
	v_rcp_f32_e32 v8, v8
	v_rcp_f32_e32 v9, v9
	v_rcp_f32_e32 v2, v2
	v_rcp_f32_e32 v3, v3
	v_rcp_f32_e32 v4, v4
	v_rcp_f32_e32 v5, v5
	v_cvt_pk_bf16_f32 v6, v6, v7
	v_cvt_pk_bf16_f32 v7, v8, v9
	v_cvt_pk_bf16_f32 v8, v2, v3
	v_cvt_pk_bf16_f32 v9, v4, v5
	ds_bpermute_b32 v236, v143, v6
	ds_bpermute_b32 v237, v143, v7
	ds_bpermute_b32 v238, v143, v8
	ds_bpermute_b32 v239, v143, v9
	s_waitcnt lgkmcnt(8)
	global_store_dwordx4 v148, v[228:231], s[18:19] offset:256
	s_waitcnt lgkmcnt(4)
	s_add_u32 s18, s4, 0x108000
	s_addc_u32 s19, s5, 0
	global_store_dwordx4 v148, v[232:235], s[18:19]
	s_waitcnt lgkmcnt(0)
	global_store_dwordx4 v148, v[236:239], s[18:19] offset:256
	s_andn2_b64 vcc, exec, s[40:41]
	s_mov_b64 s[18:19], -1
	s_cbranch_vccnz .LBB0_679
	s_andn2_b64 vcc, exec, s[2:3]
	s_cbranch_vccnz .LBB0_678
	s_barrier
	s_branch .LBB0_678
